# attention: LDS-DMA issue staggered between the two wave groups (group B issues after its softmax block)
# speedup vs baseline: 1.0182x; 1.0047x over previous
; #define LAS __attribute__((address_space(3)))
; DI void u_attn2(Frame& F, int h, int qb, int sp, int ntile) {
;     ...
;     for (int t = 0; t < ntile; ++t) {
;         const int kt = kt0 + t;
;         __syncthreads();
; #pragma unroll
;         for (int i = 0; i < 3; ++i) { const int p = tid + 512 * i, r = p / 24, cc = p - r * 24; *(LAS u32x4*)(Ks + r * 200 + cc * 8) = kreg[i]; }
; #pragma unroll
;         for (int i = 0; i < 2; ++i) { const int p = tid + 512 * i, r = p >> 3, cc = p & 7; *(LAS u32x4*)(Vs + r * 72 + cc * 8) = vreg[i]; }
;         __syncthreads();
;         if (t + 1 < ntile) AT_LOAD(kt + 1)
.LBB0_2237:
	s_barrier
	s_add_i32 s39, s47, 0xb800
	s_cmp_eq_u32 s39, 0x22800
	s_cselect_b32 s39, 0, s39
	s_add_i32 s38, s39, 0xb800
	s_cmp_eq_u32 s38, 0x22800
	s_cselect_b32 s38, 0, s38
	v_add_u32_e32 v113, s47, v187
	v_add_u32_e32 v110, s38, v116
	v_mov_b32_e32 v234, 0x42800000
	s_cmp_lt_i32 s24, 4
	s_cbranch_scc0 .Latt_gB
	s_lshl_b32 vcc_lo, s24, 10
	s_add_i32 vcc_lo, vcc_lo, s11
	s_add_i32 vcc_hi, s46, 2
	s_cmp_lt_i32 vcc_hi, s45
	s_cbranch_scc0 .Latt_vonly_A
	s_add_i32 m0, s38, vcc_lo
	s_nop 0
	global_load_lds_dwordx4 v122, s[48:49]
	s_add_i32 m0, m0, 0x2000
	s_nop 0
	global_load_lds_dwordx4 v123, s[48:49]
	s_add_i32 m0, m0, 0x2000
	s_nop 0
	global_load_lds_dwordx4 v124, s[48:49]
	s_branch .Latt_vjobs_A

; #define MFMA16(a, b, c) __builtin_amdgcn_mfma_f32_16x16x32_bf16((a), (b), (c), 0, 0, 0)
; #define AT_VLD(dst, db_) { _Pragma("unroll") for (int s2 = 0; s2 < 2; ++s2) { const LAS bf16* vp = Vs + ((db_) * 16 + lc) * 72 + 32 * s2 + 4 * g4; \
;                     const u32x2 v0 = *(const LAS u32x2*)vp, v1 = *(const LAS u32x2*)(vp + 16); const u32x4 vw = (u32x4){v0.x, v0.y, v1.x, v1.y}; dst[s2] = __builtin_bit_cast(bf16x8, vw); } }
; DI void u_attn2(Frame& F, int h, int qb, int sp, int ntile) {
;     ...
;             {
;                 bf16x8 vfr[2][2];
;     ...
;                 AT_VLD(vfr[0], 0)
; #pragma unroll
;                 for (int db = 0; db < 8; ++db) {
;                     if (db < 7) AT_VLD(vfr[(db + 1) & 1], db + 1)
; #pragma unroll
;                     for (int s2 = 0; s2 < 2; ++s2)
; #pragma unroll
;                         for (int qq = 0; qq < 2; ++qq) o[db][qq] = MFMA16(vfr[db & 1][s2], pf[qq][s2], o[db][qq]);
;                 }
.Latt_noload_A:
	s_cmp_eq_u32 s46, 0
	s_cbranch_scc1 .Latt_A_qk
	v_add3_u32 v18, s46, v181, -1
	v_cmp_le_i32_e32 vcc, v18, v180
	s_cbranch_vccz .Latt_A_qk
	ds_read_b128 v[146:149], v110 offset:26624
	ds_read_b128 v[244:247], v110 offset:26688
	ds_read_b128 v[220:223], v110 offset:29184
	ds_read_b128 v[224:227], v110 offset:29248
	s_waitcnt lgkmcnt(3)
	v_mfma_f32_16x16x32_bf16 v[134:137], v[146:149], v[198:201], v[134:137]
	v_mfma_f32_16x16x32_bf16 v[118:121], v[146:149], v[210:213], v[118:121]
	ds_read_b128 v[146:149], v110 offset:31744
	s_waitcnt lgkmcnt(3)
	v_mfma_f32_16x16x32_bf16 v[134:137], v[244:247], v[192:195], v[134:137]
	v_mfma_f32_16x16x32_bf16 v[118:121], v[244:247], v[142:145], v[118:121]
	ds_read_b128 v[244:247], v110 offset:31808
	s_waitcnt lgkmcnt(3)
	v_mfma_f32_16x16x32_bf16 v[106:109], v[220:223], v[198:201], v[106:109]
	v_mfma_f32_16x16x32_bf16 v[102:105], v[220:223], v[210:213], v[102:105]
	ds_read_b128 v[220:223], v110 offset:34304
	s_waitcnt lgkmcnt(3)
	v_mfma_f32_16x16x32_bf16 v[106:109], v[224:227], v[192:195], v[106:109]
	v_mfma_f32_16x16x32_bf16 v[102:105], v[224:227], v[142:145], v[102:105]
	ds_read_b128 v[224:227], v110 offset:34368
	s_waitcnt lgkmcnt(3)
	v_mfma_f32_16x16x32_bf16 v[98:101], v[146:149], v[198:201], v[98:101]
	v_mfma_f32_16x16x32_bf16 v[94:97], v[146:149], v[210:213], v[94:97]
	ds_read_b128 v[146:149], v110 offset:36864
	s_waitcnt lgkmcnt(3)
	v_mfma_f32_16x16x32_bf16 v[98:101], v[244:247], v[192:195], v[98:101]
	v_mfma_f32_16x16x32_bf16 v[94:97], v[244:247], v[142:145], v[94:97]
	ds_read_b128 v[244:247], v110 offset:36928
	s_waitcnt lgkmcnt(3)
	v_mfma_f32_16x16x32_bf16 v[90:93], v[220:223], v[198:201], v[90:93]
	v_mfma_f32_16x16x32_bf16 v[86:89], v[220:223], v[210:213], v[86:89]
	ds_read_b128 v[220:223], v110 offset:39424
	s_waitcnt lgkmcnt(3)
	v_mfma_f32_16x16x32_bf16 v[90:93], v[224:227], v[192:195], v[90:93]
	v_mfma_f32_16x16x32_bf16 v[86:89], v[224:227], v[142:145], v[86:89]
	ds_read_b128 v[224:227], v110 offset:39488
	s_waitcnt lgkmcnt(3)
	v_mfma_f32_16x16x32_bf16 v[82:85], v[146:149], v[198:201], v[82:85]
	v_mfma_f32_16x16x32_bf16 v[78:81], v[146:149], v[210:213], v[78:81]
	ds_read_b128 v[146:149], v110 offset:41984
	s_waitcnt lgkmcnt(3)
	v_mfma_f32_16x16x32_bf16 v[82:85], v[244:247], v[192:195], v[82:85]
	v_mfma_f32_16x16x32_bf16 v[78:81], v[244:247], v[142:145], v[78:81]
	ds_read_b128 v[244:247], v110 offset:42048
	s_waitcnt lgkmcnt(3)
	v_mfma_f32_16x16x32_bf16 v[70:73], v[220:223], v[198:201], v[70:73]
	v_mfma_f32_16x16x32_bf16 v[74:77], v[220:223], v[210:213], v[74:77]
	ds_read_b128 v[220:223], v110 offset:44544
	s_waitcnt lgkmcnt(3)
	v_mfma_f32_16x16x32_bf16 v[70:73], v[224:227], v[192:195], v[70:73]
	v_mfma_f32_16x16x32_bf16 v[74:77], v[224:227], v[142:145], v[74:77]
	ds_read_b128 v[224:227], v110 offset:44608
	s_waitcnt lgkmcnt(3)
	v_mfma_f32_16x16x32_bf16 v[66:69], v[146:149], v[198:201], v[66:69]
	v_mfma_f32_16x16x32_bf16 v[58:61], v[146:149], v[210:213], v[58:61]
	s_waitcnt lgkmcnt(2)
	v_mfma_f32_16x16x32_bf16 v[66:69], v[244:247], v[192:195], v[66:69]
	v_mfma_f32_16x16x32_bf16 v[58:61], v[244:247], v[142:145], v[58:61]
	s_waitcnt lgkmcnt(1)
	v_mfma_f32_16x16x32_bf16 v[54:57], v[220:223], v[198:201], v[54:57]
	v_mfma_f32_16x16x32_bf16 v[62:65], v[220:223], v[210:213], v[62:65]
	s_waitcnt lgkmcnt(0)
	v_mfma_f32_16x16x32_bf16 v[54:57], v[224:227], v[192:195], v[54:57]
	v_mfma_f32_16x16x32_bf16 v[62:65], v[224:227], v[142:145], v[62:65]

; DI void u_attn2(Frame& F, int h, int qb, int sp, int ntile) {
;     ...
;         if (t + 1 < ntile) AT_LOAD(kt + 1)
.Latt_B_dma:
	s_lshl_b32 vcc_lo, s24, 10
	s_add_i32 vcc_lo, vcc_lo, s11
	s_add_i32 vcc_hi, s46, 2
	s_cmp_lt_i32 vcc_hi, s45
	s_cbranch_scc0 .Latt_vonly_B
	s_add_i32 m0, s38, vcc_lo
	s_nop 0
	global_load_lds_dwordx4 v122, s[48:49]
	s_add_i32 m0, m0, 0x2000
	s_nop 0
	global_load_lds_dwordx4 v123, s[48:49]
	s_add_i32 m0, m0, 0x2000
	s_nop 0
	global_load_lds_dwordx4 v124, s[48:49]
	s_branch .Latt_vjobs_B
